# MLA task prologue: rope table rows of each axis fetched together instead of serialized load-wait-use round trips
# speedup vs baseline: 1.0028x; 1.0017x over previous
; __device__ __forceinline__ unsigned cvt_pk_bf16(float lo, float hi) { unsigned r; asm volatile("v_cvt_pk_bf16_f32 %0, %1, %2" : "=v"(r) : "v"(lo), "v"(hi)); return r; }
; __device__ __forceinline__ float bf2f(bf16_t b) { return __uint_as_float(((unsigned)b) << 16); }
; template <int MODE>
; __device__ __forceinline__ void attn_body(const Job J, char* lds) {
;     ...
;   const bf16_t* Qw = J.Qb + (size_t)(wid * QBLK + r32) * J.ldq + hi * 8;
;   char* ql = lds + 2 * SHM_V + 2 * SHM_K + NW * 256 + (wid * 8 * 64 + lane) * 16;
; #pragma unroll
;   for (int d0 = 0; d0 < NQR; ++d0) qr[d0] = *reinterpret_cast<const bf16x8*>(Qw + d0 * 16);
;   if constexpr (MODE == 2) {
; #pragma unroll
;     for (int d0 = 4; d0 < 8; ++d0) *reinterpret_cast<bf16x8*>(ql + (d0 - 4) * 1024) = *reinterpret_cast<const bf16x8*>(Qw + d0 * 16);
;     const int tok = J.tok0 + wid * QBLK + r32; const int prow = tok >> 6, pcol = tok & 63;
; #pragma unroll
;     for (int ax = 0; ax < 2; ++ax) {
;       const float* cs = J.rope + (size_t)((ax == 0 ? prow : pcol) * 16 + hi * 8) * 2;
;       bf16x8 x1 = *reinterpret_cast<const bf16x8*>(Qw + (8 + 2 * ax) * 16), x2 = *reinterpret_cast<const bf16x8*>(Qw + (9 + 2 * ax) * 16); u32x4 w1, w2;
; #pragma unroll
;       for (int i = 0; i < 4; ++i) {
;         const f32x4 t = *(const f32x4*)(cs + 4 * i);
;         const float a0 = bf2f((bf16_t)x1[2 * i]), a1 = bf2f((bf16_t)x1[2 * i + 1]), b0 = bf2f((bf16_t)x2[2 * i]), b1 = bf2f((bf16_t)x2[2 * i + 1]);
;         w1[i] = cvt_pk_bf16(a0 * t[0] - b0 * t[1], a1 * t[2] - b1 * t[3]);
;         w2[i] = cvt_pk_bf16(a0 * t[1] + b0 * t[0], a1 * t[3] + b1 * t[2]);
;       }
;       *reinterpret_cast<u32x4*>(ql + (4 + 2 * ax) * 1024) = w1; *reinterpret_cast<u32x4*>(ql + (5 + 2 * ax) * 1024) = w2;
.LBB0_1392:
	s_bfe_u32 s72, s71, 0x30003
	s_bfe_u32 s6, s71, 0x20006
	s_lshl_b32 s6, s6, 3
	s_or_b32 s72, s72, s6
	s_and_b32 s6, s71, 7
	s_lshl_b32 s6, s6, 5
	s_or_b32 s72, s72, s6
	s_and_b32 s6, s71, 0x300
	s_or_b32 s72, s72, s6
	s_ashr_i32 s6, s72, 7
	s_lshl_b32 s7, s72, 8
	s_lshl_b32 s73, s6, 11
	s_and_b32 s7, s7, 0x700
	s_or_b32 s36, s73, s7
	s_bfe_u32 s72, s72, 0x40003
	s_ashr_i32 s37, s36, 31
	s_mul_i32 s9, s36, 0x1800
	s_mul_hi_i32 s8, s36, 0x1800
	s_add_u32 s9, s0, s9
	v_mov_b32_e32 v119, v170
	s_barrier
	s_addc_u32 s38, s1, s8
	s_mul_i32 s8, s72, 0x180
	s_add_u32 s8, s9, s8
	v_ashrrev_i32_e32 v32, 6, v119
	v_and_b32_e32 v138, 31, v119
	v_lshlrev_b32_e32 v118, 5, v32
	v_or_b32_e32 v16, s7, v138
	s_addc_u32 s9, s38, 0
	v_bfe_u32 v137, v119, 5, 1
	v_add_u32_e32 v34, v16, v118
	v_or_b32_e32 v2, v118, v138
	v_mov_b64_e32 v[0:1], s[8:9]
	v_lshlrev_b32_e32 v33, 3, v137
	v_ashrrev_i32_e32 v16, 2, v34
	v_mad_i64_i32 v[0:1], s[8:9], v2, s40, v[0:1]
	v_lshlrev_b32_e32 v116, 4, v137
	v_and_or_b32 v24, v16, -16, v33
	v_lshl_add_u64 v[28:29], v[0:1], 0, v[116:117]
	v_ashrrev_i32_e32 v25, 31, v24
	global_load_dwordx4 v[0:3], v[28:29], off offset:128
	global_load_dwordx4 v[4:7], v[28:29], off offset:160
	global_load_dwordx4 v[8:11], v[28:29], off offset:192
	global_load_dwordx4 v[12:15], v[28:29], off offset:224
	global_load_dwordx4 v[16:19], v[28:29], off offset:256
	global_load_dwordx4 v[20:23], v[28:29], off offset:288
	v_lshl_add_u64 v[30:31], v[24:25], 3, s[30:31]
	global_load_dwordx4 v[24:27], v[30:31], off
	v_and_b32_e32 v120, 63, v119
	v_lshl_add_u32 v32, v32, 13, s43
	v_lshlrev_b32_e32 v121, 4, v120
	v_add_u32_e32 v142, v32, v121
	global_load_dwordx4 v[108:111], v[28:29], off
	global_load_dwordx4 v[104:107], v[28:29], off offset:32
	global_load_dwordx4 v[100:103], v[28:29], off offset:64
	global_load_dwordx4 v[96:99], v[28:29], off offset:96
	global_load_dwordx4 v[224:227], v[30:31], off offset:16
	global_load_dwordx4 v[228:231], v[30:31], off offset:32
	global_load_dwordx4 v[232:235], v[30:31], off offset:48
	v_ashrrev_i32_e32 v144, 3, v119
	v_ashrrev_i32_e32 v143, 4, v119
	s_lshl_b32 s7, s72, 9
	v_add_u32_e32 v145, 32, v143
	s_add_u32 s8, s2, s7
	v_mov_b32_e32 v115, v117
	s_addc_u32 s9, s3, 0
	v_mov_b32_e32 v113, v117
	v_lshlrev_b32_e32 v32, 1, v143
	v_mul_lo_u32 v35, v143, s41
	v_lshlrev_b32_e32 v37, 3, v144
	v_mul_lo_u32 v36, v144, s41
	v_mad_u32_u24 v122, v138, s41, 0
	v_add_u32_e32 v35, 0, v35
	v_and_b32_e32 v37, 0x70, v37
	v_add_u32_e32 v36, 0, v36
	v_add_u32_e32 v38, 0x3000, v35
	s_lshl_b32 s74, s6, 8
	s_addk_i32 s74, 0x4000
	s_cmp_lg_u32 0, -1
	s_cselect_b32 s38, 0, 0
	v_and_b32_e32 v123, 0x3fffffc0, v119
	v_lshlrev_b32_e32 v125, 1, v119
	v_and_b32_e32 v126, 0xc0, v121
	v_add_u32_e32 v178, 0xe000, v122
	v_and_b32_e32 v125, 32, v125
	s_mov_b32 s75, 2
	s_waitcnt vmcnt(13)
	ds_write_b128 v142, v[0:3]
	s_waitcnt vmcnt(12)
	ds_write_b128 v142, v[4:7] offset:1024
	s_waitcnt vmcnt(11)
	ds_write_b128 v142, v[8:11] offset:2048
	s_waitcnt vmcnt(10)
	ds_write_b128 v142, v[12:15] offset:3072
	s_waitcnt vmcnt(9)
	v_lshlrev_b32_e32 v1, 16, v16
	s_waitcnt vmcnt(8)
	v_lshlrev_b32_e32 v0, 16, v20
	v_and_b32_e32 v3, 0xffff0000, v16
	v_and_b32_e32 v2, 0xffff0000, v20
	s_waitcnt vmcnt(7)
	v_pk_mul_f32 v[4:5], v[24:25], v[0:1] op_sel:[0,1] op_sel_hi:[1,0]
	v_pk_mul_f32 v[0:1], v[24:25], v[0:1]
	v_pk_mul_f32 v[6:7], v[26:27], v[2:3] op_sel:[0,1] op_sel_hi:[1,0]
	v_pk_mul_f32 v[2:3], v[26:27], v[2:3]
	v_sub_f32_e32 v4, v4, v5
	v_add_f32_e32 v1, v1, v0
	v_sub_f32_e32 v0, v6, v7
	v_add_f32_e32 v2, v3, v2
	v_cvt_pk_bf16_f32 v0, v4, v0
	v_cvt_pk_bf16_f32 v4, v1, v2
	s_nop 0
	v_lshlrev_b32_e32 v3, 16, v17
	v_lshlrev_b32_e32 v2, 16, v21
	v_and_b32_e32 v11, 0xffff0000, v17
	v_and_b32_e32 v10, 0xffff0000, v21
	v_and_b32_e32 v15, 0xffff0000, v19
	v_and_b32_e32 v14, 0xffff0000, v23
	s_waitcnt vmcnt(2)
	v_pk_mul_f32 v[12:13], v[224:225], v[2:3] op_sel:[0,1] op_sel_hi:[1,0]
	v_pk_mul_f32 v[2:3], v[224:225], v[2:3]
	v_pk_mul_f32 v[6:7], v[226:227], v[10:11] op_sel:[0,1] op_sel_hi:[1,0]
	v_pk_mul_f32 v[8:9], v[226:227], v[10:11]
	v_sub_f32_e32 v1, v12, v13
	v_add_f32_e32 v5, v9, v8
	v_add_f32_e32 v2, v3, v2
	v_sub_f32_e32 v3, v6, v7
	v_cvt_pk_bf16_f32 v1, v1, v3
	v_cvt_pk_bf16_f32 v5, v2, v5
	s_nop 0
	v_lshlrev_b32_e32 v3, 16, v18
	v_lshlrev_b32_e32 v2, 16, v22
	v_and_b32_e32 v11, 0xffff0000, v18
	v_and_b32_e32 v10, 0xffff0000, v22
	v_lshlrev_b32_e32 v18, 4, v34
	v_and_b32_e32 v34, 3, v143
	s_waitcnt vmcnt(1)
	v_pk_mul_f32 v[12:13], v[228:229], v[2:3] op_sel:[0,1] op_sel_hi:[1,0]
	v_pk_mul_f32 v[2:3], v[228:229], v[2:3]
	v_pk_mul_f32 v[6:7], v[230:231], v[10:11] op_sel:[0,1] op_sel_hi:[1,0]
	v_pk_mul_f32 v[8:9], v[230:231], v[10:11]
	v_sub_f32_e32 v10, v12, v13
	v_add_f32_e32 v3, v3, v2
	v_sub_f32_e32 v2, v6, v7
	v_add_f32_e32 v6, v9, v8
	v_cvt_pk_bf16_f32 v2, v10, v2
	v_cvt_pk_bf16_f32 v6, v3, v6
	s_nop 0
	v_lshlrev_b32_e32 v13, 16, v19
	v_lshlrev_b32_e32 v12, 16, v23
	v_lshlrev_b32_e32 v30, 3, v119
	v_lshlrev_b32_e32 v31, 4, v119
	v_and_b32_e32 v114, 0x70, v31
	v_bitop3_b32 v146, v116, v30, s47 bitop3:0x78
	v_bitop3_b32 v37, v114, v37, s46 bitop3:0x36
	v_and_b32_e32 v31, 0x70, v30
	v_add_u32_e32 v147, v122, v146
	v_add_u32_e32 v150, v36, v37
	v_bitop3_b32 v158, v116, v31, 32 bitop3:0x36
	v_add_u32_e32 v153, v122, v158
	v_bitop3_b32 v161, v116, v31, 64 bitop3:0x36
	v_add_u32_e32 v154, v122, v161
	v_bitop3_b32 v164, v116, v31, s49 bitop3:0x36
	v_add_u32_e32 v155, v122, v164
	v_bitop3_b32 v167, v116, v31, s50 bitop3:0x36
	v_add_u32_e32 v156, v122, v167
	v_bitop3_b32 v169, v116, v31, s51 bitop3:0x36
	v_add_u32_e32 v160, v122, v169
	v_bitop3_b32 v172, v116, v31, s45 bitop3:0x36
	v_add_u32_e32 v159, v122, v172
	v_bitop3_b32 v173, v116, v31, s52 bitop3:0x36
	v_add_u32_e32 v162, v122, v173
	v_bitop3_b32 v174, v116, v31, s46 bitop3:0x36
	v_add_u32_e32 v163, v122, v174
	v_bitop3_b32 v175, v116, v31, s53 bitop3:0x36
	v_add_u32_e32 v166, v122, v175
	v_bitop3_b32 v176, v116, v31, s54 bitop3:0x36
	v_add_u32_e32 v165, v122, v176
	v_bitop3_b32 v177, v116, v31, s55 bitop3:0x36
	v_add_u32_e32 v168, v122, v177
	s_waitcnt vmcnt(0)
; __device__ __forceinline__ unsigned cvt_pk_bf16(float lo, float hi) { unsigned r; asm volatile("v_cvt_pk_bf16_f32 %0, %1, %2" : "=v"(r) : "v"(lo), "v"(hi)); return r; }
; __device__ __forceinline__ float bf2f(bf16_t b) { return __uint_as_float(((unsigned)b) << 16); }
; __device__ __forceinline__ int v_st(int k, int c) { const int kk = (k & ~0xC) | ((k & 4) << 1) | ((k & 8) >> 1); return ((kk >> 3) * 4 + (c >> 5)) * 512 + ((kk & 7) * 32 + (c & 31)) * 2; }
; __device__ __forceinline__ int v_rd_base(int lane) { return ((lane & 3) << 3) | (((lane >> 2) & 3) << 6) | (((lane >> 4) & 1) << 5) | (((lane >> 5) & 1) << 8); }
; #define SWAIT() asm volatile("s_waitcnt vmcnt(0)" ::: "memory")
; template <int MODE>
; __device__ __forceinline__ void attn_body(const Job J, char* lds) {
;     ...
;     const int tok = J.tok0 + wid * QBLK + r32; const int prow = tok >> 6, pcol = tok & 63;
; #pragma unroll
;     for (int ax = 0; ax < 2; ++ax) {
;       const float* cs = J.rope + (size_t)((ax == 0 ? prow : pcol) * 16 + hi * 8) * 2;
;       bf16x8 x1 = *reinterpret_cast<const bf16x8*>(Qw + (8 + 2 * ax) * 16), x2 = *reinterpret_cast<const bf16x8*>(Qw + (9 + 2 * ax) * 16); u32x4 w1, w2;
; #pragma unroll
;       for (int i = 0; i < 4; ++i) {
;         const f32x4 t = *(const f32x4*)(cs + 4 * i);
;         const float a0 = bf2f((bf16_t)x1[2 * i]), a1 = bf2f((bf16_t)x1[2 * i + 1]), b0 = bf2f((bf16_t)x2[2 * i]), b1 = bf2f((bf16_t)x2[2 * i + 1]);
;         w1[i] = cvt_pk_bf16(a0 * t[0] - b0 * t[1], a1 * t[2] - b1 * t[3]);
;         w2[i] = cvt_pk_bf16(a0 * t[1] + b0 * t[0], a1 * t[3] + b1 * t[2]);
;       }
;       *reinterpret_cast<u32x4*>(ql + (4 + 2 * ax) * 1024) = w1; *reinterpret_cast<u32x4*>(ql + (5 + 2 * ax) * 1024) = w2;
;     }
;   }
;   const int sr = tid >> 4, sc = (tid & 15) * 8, vst0 = v_st(sr, sc), vst1 = v_st(32 + sr, sc);
;   const int pr = tid >> 3, pc = (tid & 7) * 8;
;   const int vb0 = (int)(uintptr_t)V_lds + v_rd_base(lane);
;   bf16x8 vs0, vs1, ks0, ks1, kp;
;   const int rq = J.qb4 + (wid >> 1), qc = (wid & 1) * 32 + r32;
;   const int rs = min(max(rq - 4, 0), 24), cs_ = min(max(qc - 8, 0), 48);
;     ...
;   f32x16 pA0, pA1, pB0, pB1; float mnA, mnB, alA, alB; bf16x8 pa0, pa1, pa2, pa3; const int NT = J.NT;
;   SLOAD(0); SWAIT(); SWRITE(0); __syncthreads();
	v_pk_mul_f32 v[16:17], v[232:233], v[12:13] op_sel:[0,1] op_sel_hi:[1,0]
	v_pk_mul_f32 v[8:9], v[232:233], v[12:13]
	v_pk_mul_f32 v[12:13], v[234:235], v[14:15] op_sel:[0,1] op_sel_hi:[1,0]
	v_pk_mul_f32 v[10:11], v[234:235], v[14:15]
	v_sub_f32_e32 v3, v16, v17
	v_add_f32_e32 v7, v9, v8
	v_sub_f32_e32 v8, v12, v13
	v_add_f32_e32 v9, v11, v10
	v_and_or_b32 v16, v18, s44, v33
	v_cvt_pk_bf16_f32 v3, v3, v8
	v_cvt_pk_bf16_f32 v7, v7, v9
	global_load_dwordx4 v[8:11], v[28:29], off offset:320
	global_load_dwordx4 v[12:15], v[28:29], off offset:352
	v_lshlrev_b32_e32 v20, 3, v16
	global_load_dwordx4 v[16:19], v20, s[30:31]
	global_load_dwordx4 v[236:239], v20, s[30:31] offset:16
	global_load_dwordx4 v[240:243], v20, s[30:31] offset:32
	global_load_dwordx4 v[244:247], v20, s[30:31] offset:48
	ds_write_b128 v142, v[0:3] offset:4096
	ds_write_b128 v142, v[4:7] offset:5120
	v_lshrrev_b32_e32 v33, 1, v143
	s_waitcnt vmcnt(5)
	v_lshlrev_b32_e32 v1, 16, v8
	s_waitcnt vmcnt(4)
	v_lshlrev_b32_e32 v0, 16, v12
	v_and_b32_e32 v3, 0xffff0000, v8
	v_and_b32_e32 v2, 0xffff0000, v12
	s_waitcnt vmcnt(3)
	v_pk_mul_f32 v[4:5], v[16:17], v[0:1] op_sel:[0,1] op_sel_hi:[1,0]
	v_pk_mul_f32 v[0:1], v[16:17], v[0:1]
	v_pk_mul_f32 v[6:7], v[18:19], v[2:3] op_sel:[0,1] op_sel_hi:[1,0]
	v_pk_mul_f32 v[2:3], v[18:19], v[2:3]
	v_sub_f32_e32 v4, v4, v5
	v_add_f32_e32 v0, v1, v0
	v_sub_f32_e32 v1, v6, v7
	v_add_f32_e32 v2, v3, v2
	v_cvt_pk_bf16_f32 v4, v4, v1
	v_cvt_pk_bf16_f32 v0, v0, v2
	s_nop 0
	v_lshlrev_b32_e32 v3, 16, v9
	v_lshlrev_b32_e32 v2, 16, v13
	v_and_b32_e32 v7, 0xffff0000, v9
	v_and_b32_e32 v6, 0xffff0000, v13
	s_waitcnt vmcnt(2)
	v_pk_mul_f32 v[8:9], v[236:237], v[2:3] op_sel:[0,1] op_sel_hi:[1,0]
	v_pk_mul_f32 v[12:13], v[238:239], v[6:7] op_sel:[0,1] op_sel_hi:[1,0]
	v_pk_mul_f32 v[6:7], v[238:239], v[6:7]
	v_pk_mul_f32 v[2:3], v[236:237], v[2:3]
	v_sub_f32_e32 v1, v8, v9
	v_add_f32_e32 v6, v7, v6
	v_add_f32_e32 v2, v3, v2
	v_sub_f32_e32 v3, v12, v13
	v_cvt_pk_bf16_f32 v5, v1, v3
	v_cvt_pk_bf16_f32 v1, v2, v6
	s_nop 0
	v_lshlrev_b32_e32 v3, 16, v10
	v_lshlrev_b32_e32 v2, 16, v14
	v_and_b32_e32 v13, 0xffff0000, v10
	v_and_b32_e32 v12, 0xffff0000, v14
	s_waitcnt vmcnt(1)
	v_pk_mul_f32 v[16:17], v[240:241], v[2:3] op_sel:[0,1] op_sel_hi:[1,0]
	v_pk_mul_f32 v[2:3], v[240:241], v[2:3]
	v_pk_mul_f32 v[6:7], v[242:243], v[12:13] op_sel:[0,1] op_sel_hi:[1,0]
	v_pk_mul_f32 v[8:9], v[242:243], v[12:13]
	v_add_f32_e32 v2, v3, v2
	v_sub_f32_e32 v10, v16, v17
	v_sub_f32_e32 v3, v6, v7
	v_add_f32_e32 v7, v9, v8
	v_cvt_pk_bf16_f32 v6, v10, v3
	v_cvt_pk_bf16_f32 v2, v2, v7
	s_nop 0
	v_add_u32_e32 v12, s73, v144
	v_add_u32_e32 v8, s73, v143
	v_ashrrev_i32_e32 v13, 31, v12
	v_ashrrev_i32_e32 v9, 31, v8
	v_lshlrev_b64 v[12:13], 7, v[12:13]
	v_and_b32_e32 v3, 0x78, v30
	v_add_u32_e32 v20, s73, v145
	v_lshlrev_b64 v[22:23], 13, v[8:9]
	v_lshl_add_u64 v[12:13], s[10:11], 0, v[12:13]
	v_lshlrev_b32_e32 v112, 1, v3
	v_ashrrev_i32_e32 v21, 31, v20
	v_lshl_add_u64 v[26:27], v[12:13], 0, v[114:115]
	v_lshl_add_u64 v[12:13], s[8:9], 0, v[22:23]
	v_lshlrev_b64 v[20:21], 13, v[20:21]
	v_lshl_add_u64 v[22:23], v[12:13], 0, v[112:113]
	v_lshlrev_b32_e32 v13, 16, v11
	v_lshlrev_b32_e32 v12, 16, v15
	v_and_b32_e32 v11, 0xffff0000, v11
	v_and_b32_e32 v10, 0xffff0000, v15
	v_lshl_add_u64 v[20:21], s[8:9], 0, v[20:21]
	v_lshl_add_u64 v[24:25], v[20:21], 0, v[112:113]
	v_bfe_u32 v30, v30, 5, 2
	s_waitcnt vmcnt(0)
	v_pk_mul_f32 v[14:15], v[244:245], v[12:13] op_sel:[0,1] op_sel_hi:[1,0]
	v_pk_mul_f32 v[12:13], v[244:245], v[12:13]
	v_pk_mul_f32 v[16:17], v[246:247], v[10:11] op_sel:[0,1] op_sel_hi:[1,0]
	v_pk_mul_f32 v[10:11], v[246:247], v[10:11]
	v_sub_f32_e32 v3, v14, v15
	v_sub_f32_e32 v7, v16, v17
	v_add_f32_e32 v10, v11, v10
	v_add_f32_e32 v9, v13, v12
	v_cvt_pk_bf16_f32 v7, v3, v7
	v_cvt_pk_bf16_f32 v3, v9, v10
	global_load_dwordx4 v[10:13], v[22:23], off offset:256
	global_load_dwordx4 v[14:17], v[24:25], off offset:256
	global_load_dwordx4 v[18:21], v[22:23], off
	s_nop 0
	global_load_dwordx4 v[22:25], v[24:25], off
	s_nop 0
	global_load_dwordx4 v[26:29], v[26:27], off
	v_and_b32_e32 v9, 0xfffff0, v143
	v_and_or_b32 v9, v32, 8, v9
	v_and_or_b32 v32, v33, 4, v34
	v_and_b32_e32 v33, 0xfffff0, v145
	v_lshlrev_b32_e32 v34, 1, v145
	v_lshrrev_b32_e32 v9, 1, v9
	v_and_or_b32 v33, v34, 8, v33
	v_or_b32_e32 v9, v9, v30
	v_lshrrev_b32_e32 v33, 1, v33
	v_lshlrev_b32_e32 v31, 6, v32
	v_and_b32_e32 v32, 48, v112
	v_lshlrev_b32_e32 v9, 9, v9
	v_or_b32_e32 v30, v33, v30
	v_or3_b32 v9, v9, v31, v32
	v_lshlrev_b32_e32 v30, 9, v30
	v_lshrrev_b32_e32 v34, 1, v119
	v_bitop3_b32 v34, v112, v34, s47 bitop3:0x78
	v_or3_b32 v30, v30, v31, v32
	v_add_u32_e32 v151, 0, v9
	ds_write_b128 v142, v[4:7] offset:6144
	ds_write_b128 v142, v[0:3] offset:7168
	v_add_u32_e32 v148, v35, v34
	v_add_u32_e32 v149, v38, v34
	v_add_u32_e32 v152, 0, v30
	s_waitcnt vmcnt(0)
	s_waitcnt vmcnt(4)
	ds_write_b128 v151, v[10:13]
	s_waitcnt vmcnt(3)
	ds_write_b128 v152, v[14:17]
	s_waitcnt vmcnt(2)
	ds_write_b128 v148, v[18:21] offset:32768
	s_waitcnt vmcnt(1)
	ds_write_b128 v149, v[22:25] offset:32768
	s_waitcnt vmcnt(0)
	ds_write_b128 v150, v[26:29] offset:32768
	s_waitcnt lgkmcnt(0)
	s_barrier
; template <int DQK>
; __device__ __forceinline__ void qkt(f32x16& p0, f32x16& p1, const char* Ks, const bf16x8* qr, const char* ql, int r32, int hi) {
;   p0 = f32x16{}; p1 = f32x16{};
; #pragma unroll
;   for (int d0 = 0; d0 < DQK / 16; ++d0) { const int cb = (d0 * 16 + hi * 8) * 2;
;     bf16x8 b0 = *reinterpret_cast<const bf16x8*>(Ks + r32 * (DQK * 2) + (cb ^ ((r32 & 7) << 4)));
;     bf16x8 b1 = *reinterpret_cast<const bf16x8*>(Ks + (32 + r32) * (DQK * 2) + (cb ^ ((r32 & 7) << 4)));
;     constexpr int NQR = DQK == 192 ? 4 : 8;
;     bf16x8 qv; if (d0 < NQR) qv = qr[d0 < NQR ? d0 : 0]; else qv = *reinterpret_cast<const bf16x8*>(ql + (d0 - NQR) * 1024);
;     p0 = __builtin_amdgcn_mfma_f32_32x32x16_bf16(b0, qv, p0, 0, 0, 0);
;     p1 = __builtin_amdgcn_mfma_f32_32x32x16_bf16(b1, qv, p1, 0, 0, 0); }
; }
; template <int MODE>
; __device__ __forceinline__ void attn_body(const Job J, char* lds) {
;     ...
;   qkt<DQK>(pA0, pA1, K_lds, qr, ql, r32, hi); MASK(pA0, pA1, 0); partialSM(pA0, pA1, m_reg, mnA, alA, C, THRS);
;   SLOAD(1);
	ds_read_b128 v[0:3], v147 offset:32768
	ds_read_b128 v[4:7], v147 offset:45056
	s_waitcnt lgkmcnt(1)
	v_mfma_f32_32x32x16_bf16 v[64:79], v[0:3], v[108:111], 0
	v_lshl_add_u32 v119, v123, 2, s42
	v_lshlrev_b32_e32 v123, 3, v120
	v_and_b32_e32 v127, 0x100, v123
	v_lshl_add_u32 v139, v138, 2, v119
	s_waitcnt lgkmcnt(0)
	v_mfma_f32_32x32x16_bf16 v[80:95], v[4:7], v[108:111], 0
	ds_read_b128 v[0:3], v153 offset:32768
	ds_read_b128 v[4:7], v153 offset:45056
	s_waitcnt lgkmcnt(1)
	v_mfma_f32_32x32x16_bf16 v[64:79], v[0:3], v[104:107], v[64:79]
	s_waitcnt lgkmcnt(0)
	v_mfma_f32_32x32x16_bf16 v[80:95], v[4:7], v[104:107], v[80:95]
	ds_read_b128 v[0:3], v154 offset:32768
	ds_read_b128 v[4:7], v154 offset:45056
	s_waitcnt lgkmcnt(1)
	v_mfma_f32_32x32x16_bf16 v[64:79], v[0:3], v[100:103], v[64:79]
	s_waitcnt lgkmcnt(0)
	v_mfma_f32_32x32x16_bf16 v[80:95], v[4:7], v[100:103], v[80:95]
	ds_read_b128 v[0:3], v155 offset:32768
	ds_read_b128 v[4:7], v155 offset:45056
	s_waitcnt lgkmcnt(1)
	v_mfma_f32_32x32x16_bf16 v[64:79], v[0:3], v[96:99], v[64:79]
	s_waitcnt lgkmcnt(0)
	v_mfma_f32_32x32x16_bf16 v[80:95], v[4:7], v[96:99], v[80:95]
	ds_read_b128 v[0:3], v156 offset:32768
	ds_read_b128 v[4:7], v142
	ds_read_b128 v[10:13], v156 offset:45056
	ds_read_b128 v[14:17], v142 offset:1024
	s_waitcnt lgkmcnt(2)
	v_mfma_f32_32x32x16_bf16 v[64:79], v[0:3], v[4:7], v[64:79]
	s_waitcnt lgkmcnt(1)
	v_mfma_f32_32x32x16_bf16 v[80:95], v[10:13], v[4:7], v[80:95]
	ds_read_b128 v[0:3], v160 offset:32768
	ds_read_b128 v[4:7], v160 offset:45056
	s_waitcnt lgkmcnt(1)
	v_mfma_f32_32x32x16_bf16 v[64:79], v[0:3], v[14:17], v[64:79]
	s_waitcnt lgkmcnt(0)
	v_mfma_f32_32x32x16_bf16 v[80:95], v[4:7], v[14:17], v[80:95]
	ds_read_b128 v[0:3], v159 offset:32768
	ds_read_b128 v[4:7], v142 offset:2048
	ds_read_b128 v[10:13], v159 offset:45056
	ds_read_b128 v[14:17], v142 offset:3072
	s_waitcnt lgkmcnt(2)
	v_mfma_f32_32x32x16_bf16 v[64:79], v[0:3], v[4:7], v[64:79]
	s_waitcnt lgkmcnt(1)
	v_mfma_f32_32x32x16_bf16 v[80:95], v[10:13], v[4:7], v[80:95]
	ds_read_b128 v[0:3], v162 offset:32768
	ds_read_b128 v[4:7], v162 offset:45056
	s_waitcnt lgkmcnt(1)
	v_mfma_f32_32x32x16_bf16 v[64:79], v[0:3], v[14:17], v[64:79]
	s_waitcnt lgkmcnt(0)
	v_mfma_f32_32x32x16_bf16 v[80:95], v[4:7], v[14:17], v[80:95]
	ds_read_b128 v[0:3], v163 offset:32768
	ds_read_b128 v[4:7], v142 offset:4096
	ds_read_b128 v[10:13], v163 offset:45056
	ds_read_b128 v[14:17], v142 offset:5120
	s_waitcnt lgkmcnt(2)
	v_mfma_f32_32x32x16_bf16 v[64:79], v[0:3], v[4:7], v[64:79]
	s_waitcnt lgkmcnt(1)
	v_mfma_f32_32x32x16_bf16 v[80:95], v[10:13], v[4:7], v[80:95]
	ds_read_b128 v[0:3], v166 offset:32768
	ds_read_b128 v[4:7], v166 offset:45056
	s_waitcnt lgkmcnt(1)
	v_mfma_f32_32x32x16_bf16 v[64:79], v[0:3], v[14:17], v[64:79]
	s_waitcnt lgkmcnt(0)
	v_mfma_f32_32x32x16_bf16 v[80:95], v[4:7], v[14:17], v[80:95]
	ds_read_b128 v[0:3], v165 offset:32768
	ds_read_b128 v[4:7], v142 offset:6144
	ds_read_b128 v[10:13], v165 offset:45056
	ds_read_b128 v[14:17], v142 offset:7168
	s_waitcnt lgkmcnt(2)
	v_mfma_f32_32x32x16_bf16 v[64:79], v[0:3], v[4:7], v[64:79]
	ds_read_b128 v[0:3], v168 offset:32768
	s_waitcnt lgkmcnt(2)
	v_mfma_f32_32x32x16_bf16 v[80:95], v[10:13], v[4:7], v[80:95]
	v_add_u32_e32 v4, 0x60, v8
	v_ashrrev_i32_e32 v5, 31, v4
	v_lshlrev_b64 v[8:9], 13, v[4:5]
	ds_read_b128 v[4:7], v168 offset:45056
	s_waitcnt lgkmcnt(1)
	v_mfma_f32_32x32x16_bf16 v[64:79], v[0:3], v[14:17], v[64:79]
	v_lshl_add_u64 v[0:1], s[8:9], 0, v[8:9]
	v_lshl_add_u64 v[0:1], v[0:1], 0, v[112:113]
	global_load_dwordx4 v[180:183], v[0:1], off offset:256
	global_load_dwordx4 v[186:189], v[0:1], off
	s_waitcnt lgkmcnt(0)
; #define SWAIT() asm volatile("s_waitcnt vmcnt(0)" ::: "memory")
; __device__ __forceinline__ void partialSM(f32x16& p0, f32x16& p1, float& m_reg, float& mn, float& alpha, const float C, const float THRS) {
;   float pmax = p0[0];
; #pragma unroll
;   for (int r = 1; r < 16; ++r) pmax = fmaxf(pmax, p0[r]);
; #pragma unroll
;   for (int r = 0; r < 16; ++r) pmax = fmaxf(pmax, p1[r]);
;   { auto rr = __builtin_amdgcn_permlane32_swap(__float_as_uint(pmax), __float_as_uint(pmax), false, false);
;     pmax = fmaxf(__uint_as_float(rr[0]), __uint_as_float(rr[1])); }
;   if (__builtin_expect(__all(pmax - m_reg <= THRS), 1)) { mn = m_reg; alpha = 1.f; }
;   else { mn = fmaxf(m_reg, pmax); alpha = __builtin_amdgcn_exp2f((m_reg - mn) * C); m_reg = mn; }
;   float mnC = -mn * C;
; #pragma unroll
;   for (int r = 0; r < 16; ++r) p0[r] = fmaf(p0[r], C, mnC);
; #pragma unroll
;   for (int r = 0; r < 16; ++r) p1[r] = fmaf(p1[r], C, mnC);
; #pragma unroll
;   for (int r = 0; r < 16; ++r) p0[r] = __builtin_amdgcn_exp2f(p0[r]);
; }
; template <int MODE>
; __device__ __forceinline__ void attn_body(const Job J, char* lds) {
;     ...
;   qkt<DQK>(pA0, pA1, K_lds, qr, ql, r32, hi); MASK(pA0, pA1, 0); partialSM(pA0, pA1, m_reg, mnA, alA, C, THRS);
;   SLOAD(1);
;   SWAIT(); SWRITE(1); __syncthreads();
	v_mfma_f32_32x32x16_bf16 v[80:95], v[4:7], v[14:17], v[80:95]
	s_nop 5
	v_max_f32_e32 v0, v65, v65
	v_max_f32_e32 v1, v64, v64
	v_max_f32_e32 v0, v1, v0
	v_max3_f32 v0, v0, v66, v67
	v_max3_f32 v0, v0, v68, v69
	v_max3_f32 v0, v0, v70, v71
	v_max3_f32 v0, v0, v72, v73
	v_max3_f32 v0, v0, v74, v75
	v_max3_f32 v0, v0, v76, v77
	v_max3_f32 v0, v0, v78, v79
	v_max3_f32 v0, v0, v80, v81
	v_max3_f32 v0, v0, v82, v83
	v_max3_f32 v0, v0, v84, v85
	v_max3_f32 v0, v0, v86, v87
	v_max3_f32 v0, v0, v88, v89
	v_max3_f32 v0, v0, v90, v91
	v_max3_f32 v0, v0, v92, v93
	v_max3_f32 v0, v0, v94, v95
	v_mov_b32_e32 v1, v0
	s_nop 1
	v_permlane32_swap_b32_e32 v0, v1
	v_max_f32_e32 v1, v1, v1
	v_max_f32_e32 v0, v0, v0
	v_max_f32_e32 v0, v0, v1
	v_add_f32_e32 v1, 0x7149f2ca, v0
	v_cmp_ge_f32_e32 vcc, s56, v1
	s_cmp_eq_u64 vcc, exec
	s_cselect_b64 vcc, -1, 0
	s_or_b32 s6, s73, 64
	v_max_f32_e32 v124, 0xf149f2ca, v0
	v_add_u32_e32 v0, s6, v143
	v_ashrrev_i32_e32 v1, 31, v0
	v_lshlrev_b64 v[0:1], 13, v[0:1]
	v_lshl_add_u64 v[0:1], s[8:9], 0, v[0:1]
	v_add_u32_e32 v2, s6, v144
	v_lshl_add_u64 v[0:1], v[0:1], 0, v[112:113]
	v_ashrrev_i32_e32 v3, 31, v2
	global_load_dwordx4 v[190:193], v[0:1], off offset:256
	global_load_dwordx4 v[214:217], v[0:1], off
	v_lshlrev_b64 v[2:3], 7, v[2:3]
	v_lshl_add_u64 v[2:3], s[10:11], 0, v[2:3]
	v_lshl_add_u64 v[0:1], v[2:3], 0, v[114:115]
	global_load_dwordx4 v[218:221], v[0:1], off
	v_cndmask_b32_e32 v184, v124, v136, vcc
	v_cmp_gt_u32_e64 s[6:7], 32, v120
	v_lshl_add_u64 v[120:121], s[10:11], 0, v[114:115]
	v_and_or_b32 v114, v123, 24, v126
	v_lshl_add_u64 v[122:123], s[8:9], 0, v[112:113]
	v_sub_f32_e32 v112, 0xf149f2ca, v124
	v_mul_f32_e32 v130, 0xbdd53b94, v184
	v_mul_f32_e32 v112, 0x3dd53b94, v112
	v_mov_b32_e32 v185, v130
	v_exp_f32_e32 v141, v112
	v_fmamk_f32 v64, v64, 0x3dd53b94, v130
	v_fmamk_f32 v65, v65, 0x3dd53b94, v130
	v_fmamk_f32 v66, v66, 0x3dd53b94, v130
	v_fmamk_f32 v67, v67, 0x3dd53b94, v130
	v_fmamk_f32 v68, v68, 0x3dd53b94, v130
	v_fmamk_f32 v69, v69, 0x3dd53b94, v130
	v_fmamk_f32 v70, v70, 0x3dd53b94, v130
	v_fmamk_f32 v71, v71, 0x3dd53b94, v130
	v_fmamk_f32 v72, v72, 0x3dd53b94, v130
	v_fmamk_f32 v73, v73, 0x3dd53b94, v130
	v_fmamk_f32 v74, v74, 0x3dd53b94, v130
	v_fmamk_f32 v75, v75, 0x3dd53b94, v130
	v_fmamk_f32 v76, v76, 0x3dd53b94, v130
	v_fmamk_f32 v77, v77, 0x3dd53b94, v130
	v_fmamk_f32 v78, v78, 0x3dd53b94, v130
	v_fmac_f32_e32 v185, 0x3dd53b94, v79
	v_mov_b64_e32 v[0:1], s[12:13]
	v_exp_f32_e32 v210, v64
	v_exp_f32_e32 v212, v65
	v_exp_f32_e32 v208, v66
	v_exp_f32_e32 v211, v67
	v_exp_f32_e32 v207, v68
	v_exp_f32_e32 v209, v69
	v_exp_f32_e32 v205, v70
	v_exp_f32_e32 v206, v71
	v_exp_f32_e32 v202, v72
	v_exp_f32_e32 v204, v73
	v_exp_f32_e32 v201, v74
	v_exp_f32_e32 v203, v75
	v_exp_f32_e32 v198, v76
	v_exp_f32_e32 v200, v77
	v_exp_f32_e32 v197, v78
	v_exp_f32_e32 v199, v185
	v_mov_b64_e32 v[14:15], s[26:27]
	v_or3_b32 v114, v114, v125, v127
	s_waitcnt vmcnt(0)
	v_mov_b64_e32 v[2:3], s[14:15]
	v_mov_b64_e32 v[4:5], s[16:17]
	v_mov_b64_e32 v[6:7], s[18:19]
	v_mov_b64_e32 v[8:9], s[20:21]
	v_mov_b64_e32 v[10:11], s[22:23]
	v_mov_b64_e32 v[12:13], s[24:25]
	v_mov_b64_e32 v[62:63], v[14:15]
	v_mov_b64_e32 v[46:47], v[14:15]
	v_mov_b64_e32 v[30:31], v[14:15]
	v_add_u32_e32 v157, s38, v114
	s_addk_i32 s38, 0x4000
	v_mov_b64_e32 v[60:61], v[12:13]
	v_mov_b64_e32 v[58:59], v[10:11]
	v_mov_b64_e32 v[56:57], v[8:9]
	v_mov_b64_e32 v[54:55], v[6:7]
	v_mov_b64_e32 v[52:53], v[4:5]
	v_mov_b64_e32 v[50:51], v[2:3]
	v_mov_b64_e32 v[48:49], v[0:1]
	v_mov_b64_e32 v[44:45], v[12:13]
	v_mov_b64_e32 v[42:43], v[10:11]
	v_mov_b64_e32 v[40:41], v[8:9]
	v_mov_b64_e32 v[38:39], v[6:7]
	v_mov_b64_e32 v[36:37], v[4:5]
	v_mov_b64_e32 v[34:35], v[2:3]
	v_mov_b64_e32 v[32:33], v[0:1]
	v_mov_b64_e32 v[28:29], v[12:13]
	v_mov_b64_e32 v[26:27], v[10:11]
	v_mov_b64_e32 v[24:25], v[8:9]
	v_mov_b64_e32 v[22:23], v[6:7]
	v_mov_b64_e32 v[20:21], v[4:5]
	v_mov_b64_e32 v[18:19], v[2:3]
	v_mov_b64_e32 v[16:17], v[0:1]
	v_add_u32_e32 v140, s38, v114
	v_pk_fma_f32 v[126:127], v[94:95], s[34:35], v[130:131] op_sel_hi:[1,0,0]
	v_pk_fma_f32 v[132:133], v[92:93], s[34:35], v[130:131] op_sel_hi:[1,0,0]
	v_pk_fma_f32 v[134:135], v[90:91], s[34:35], v[130:131] op_sel_hi:[1,0,0]
	v_pk_fma_f32 v[112:113], v[88:89], s[34:35], v[130:131] op_sel_hi:[1,0,0]
	v_pk_fma_f32 v[114:115], v[86:87], s[34:35], v[130:131] op_sel_hi:[1,0,0]
	v_pk_fma_f32 v[124:125], v[84:85], s[34:35], v[130:131] op_sel_hi:[1,0,0]
	v_pk_fma_f32 v[128:129], v[82:83], s[34:35], v[130:131] op_sel_hi:[1,0,0]
	v_pk_fma_f32 v[130:131], v[80:81], s[34:35], v[130:131] op_sel_hi:[1,0,0]
	v_cndmask_b32_e64 v179, v141, 1.0, vcc
	v_mov_b32_e32 v141, 0
	s_waitcnt vmcnt(2)
	ds_write_b128 v151, v[190:193] offset:16384
	ds_write_b128 v152, v[180:183] offset:16384
	s_waitcnt vmcnt(1)
	ds_write_b128 v148, v[214:217] offset:57344
	ds_write_b128 v149, v[186:189] offset:57344
	s_waitcnt vmcnt(0)
	ds_write_b128 v150, v[218:221] offset:57344
	s_waitcnt lgkmcnt(0)
	s_barrier
